# attention item prologue: Q raw loads and qn/kn gain loads issued in one batch instead of a load-wait-use chain
# baseline (speedup 1.0000x reference)
; __device__ __forceinline__ unsigned cvt_pk_bf16(float lo, float hi) { unsigned r; asm("v_cvt_pk_bf16_f32 %0, %1, %2" : "=v"(r) : "v"(lo), "v"(hi)); return r; }
; __device__ __forceinline__ float lo_bf(unsigned u) { return __uint_as_float(u << 16); }
; __device__ __forceinline__ float hi_bf(unsigned u) { return __uint_as_float(u & 0xffff0000u); }
; __device__ __forceinline__ void attn_phase(const Params& p, int l, bf16_t* PROJ, LAS unsigned char* L) {
;     ...
;         const int n = item >> 2, hp = item & 3, h = hp * 2 + hh;
;         __syncthreads();
;         for (int i = tid; i < 640; i += 512) { const int h2 = i / 320, k = i - h2 * 320; relb[i] = p.rel_bias[(size_t)(l * 8 + hp * 2 + h2) * 513 + 193 + k] * 1.4426950408889634f; }
;         bf16x8 aq[4];
;         {
;             const bf16_t* qp = PROJ + (size_t)(n * 64 + rt * 16 + fr) * INW + AQ + h * 128 + fq * 8;
;             u32x4 raw[4]; float ss = 0.f;
; #pragma unroll
;             for (int ks = 0; ks < 4; ++ks) { raw[ks] = *(const u32x4*)(qp + ks * 32);
; #pragma unroll
;                 for (int e = 0; e < 4; ++e) { const float a = lo_bf(raw[ks][e]), b = hi_bf(raw[ks][e]); ss += a * a + b * b; } }
;             ss += __shfl_xor(ss, 16); ss += __shfl_xor(ss, 32);
;             const float rs = rsqrtf(ss * (1.0f / 128.0f) + EPS) * (0.08838834764831845f * 1.4426950408889634f);
; #pragma unroll
;             for (int ks = 0; ks < 4; ++ks) { const float* gp = gq + ks * 32 + fq * 8; const float* gkp = gk + ks * 32 + fq * 8; u32x4 w;
; #pragma unroll
;                 for (int e = 0; e < 4; ++e) w[e] = cvt_pk_bf16(lo_bf(raw[ks][e]) * rs * gp[2 * e] * gkp[2 * e], hi_bf(raw[ks][e]) * rs * gp[2 * e + 1] * gkp[2 * e + 1]);
;                 aq[ks] = __builtin_bit_cast(bf16x8, w); }
.LBB0_346:
	s_or_b64 exec, exec, s[20:21]
	s_bfe_u32 s20, s43, 0x50003
	s_bfe_u32 s21, s43, 0x10002
	s_lshl_b32 s21, s21, 5
	s_or_b32 s20, s20, s21
	s_bfe_u32 s21, s43, 0x20008
	s_lshl_b32 s21, s21, 6
	s_or_b32 s20, s20, s21
	v_lshl_or_b32 v216, s20, 6, v151
	v_or_b32_e32 v2, v216, v103
	v_mov_b64_e32 v[0:1], s[14:15]
	v_add_lshl_u32 v114, s36, v150, 7
	v_mad_i64_i32 v[0:1], s[22:23], v2, s62, v[0:1]
	v_ashrrev_i32_e32 v115, 31, v114
	v_lshl_add_u64 v[0:1], v[114:115], 1, v[0:1]
	v_mov_b32_e32 v113, v137
	v_lshl_add_u64 v[0:1], v[0:1], 0, v[112:113]
	global_load_dwordx4 v[2:5], v[0:1], off
	global_load_dwordx4 v[226:229], v[0:1], off offset:64
	global_load_dwordx4 v[230:233], v[0:1], off offset:128
	global_load_dwordx4 v[30:33], v[0:1], off offset:192
	global_load_dwordx4 v[34:37], v[100:101], off
	s_sub_i32 s3, 8, s20
	s_cmp_lt_i32 s20, 8
	s_cselect_b32 s3, s3, 0
	v_mov_b32_e32 v119, 0
	s_cmp_lt_i32 s3, 9
	v_mov_b32_e32 v118, v119
	v_mov_b32_e32 v117, v119
	v_mov_b32_e32 v116, v119
	v_mov_b32_e32 v43, v119
	v_mov_b32_e32 v47, v119
	v_mov_b32_e32 v46, v119
	v_mov_b32_e32 v45, v119
	v_mov_b32_e32 v44, v119
	s_waitcnt vmcnt(0)
	v_and_b32_e32 v38, 0xffff0000, v2
	v_and_b32_e32 v40, 0xffff0000, v3
	v_lshlrev_b32_e32 v29, 16, v2
	v_mul_f32_e32 v2, v38, v38
	v_lshlrev_b32_e32 v39, 16, v3
	v_mul_f32_e32 v3, v40, v40
	v_fmac_f32_e32 v2, v29, v29
	v_fmac_f32_e32 v3, v39, v39
	v_add_f32_e32 v3, v2, v3
	v_and_b32_e32 v2, 0xffff0000, v4
	v_lshlrev_b32_e32 v41, 16, v4
	v_mul_f32_e32 v4, v2, v2
	v_fmac_f32_e32 v4, v41, v41
	v_add_f32_e32 v6, v4, v3
	v_and_b32_e32 v3, 0xffff0000, v5
	v_lshlrev_b32_e32 v4, 16, v5
	v_mul_f32_e32 v5, v3, v3
	v_fmac_f32_e32 v5, v4, v4
	v_add_f32_e32 v5, v5, v6
	v_mov_b32_e32 v6, v226
	v_mov_b32_e32 v7, v227
	v_mov_b32_e32 v8, v228
	v_mov_b32_e32 v9, v229
	s_waitcnt vmcnt(2)
	v_lshlrev_b32_e32 v17, 16, v31
	v_lshlrev_b32_e32 v25, 16, v33
	v_lshlrev_b32_e32 v24, 16, v32
	v_and_b32_e32 v23, 0xffff0000, v33
	s_waitcnt vmcnt(0)
	v_and_b32_e32 v27, 0xffff0000, v6
	v_lshlrev_b32_e32 v42, 16, v6
	v_mul_f32_e32 v6, v27, v27
	v_fmac_f32_e32 v6, v42, v42
	v_add_f32_e32 v6, v6, v5
	v_and_b32_e32 v5, 0xffff0000, v7
	v_lshlrev_b32_e32 v28, 16, v7
	v_mul_f32_e32 v7, v5, v5
	v_fmac_f32_e32 v7, v28, v28
	v_add_f32_e32 v7, v7, v6
	v_and_b32_e32 v6, 0xffff0000, v8
	v_lshlrev_b32_e32 v21, 16, v8
	v_mul_f32_e32 v8, v6, v6
	v_fmac_f32_e32 v8, v21, v21
	v_add_f32_e32 v8, v8, v7
	v_and_b32_e32 v7, 0xffff0000, v9
	v_lshlrev_b32_e32 v20, 16, v9
	v_mul_f32_e32 v9, v7, v7
	v_fmac_f32_e32 v9, v20, v20
	v_add_f32_e32 v14, v9, v8
	v_mov_b32_e32 v8, v230
	v_mov_b32_e32 v9, v231
	v_mov_b32_e32 v10, v232
	v_mov_b32_e32 v11, v233
	s_waitcnt vmcnt(0)
	v_lshlrev_b32_e32 v19, 16, v9
	v_lshlrev_b32_e32 v18, 16, v8
	v_and_b32_e32 v9, 0xffff0000, v9
	v_and_b32_e32 v8, 0xffff0000, v8
	v_pk_mul_f32 v[12:13], v[8:9], v[8:9]
	s_nop 0
	v_pk_fma_f32 v[12:13], v[18:19], v[18:19], v[12:13]
	s_nop 0
	v_add_f32_e32 v12, v12, v14
	v_add_f32_e32 v16, v13, v12
	v_lshlrev_b32_e32 v13, 16, v11
	v_lshlrev_b32_e32 v12, 16, v10
	v_and_b32_e32 v11, 0xffff0000, v11
	v_and_b32_e32 v10, 0xffff0000, v10
	v_pk_mul_f32 v[14:15], v[10:11], v[10:11]
	s_nop 0
	v_pk_fma_f32 v[14:15], v[12:13], v[12:13], v[14:15]
	s_nop 0
	v_add_f32_e32 v14, v14, v16
	v_add_f32_e32 v22, v15, v14
	v_and_b32_e32 v15, 0xffff0000, v31
	v_and_b32_e32 v14, 0xffff0000, v30
	v_lshlrev_b32_e32 v16, 16, v30
	v_pk_mul_f32 v[0:1], v[14:15], v[14:15]
	s_nop 0
	v_pk_fma_f32 v[0:1], v[16:17], v[16:17], v[0:1]
	s_nop 0
	v_add_f32_e32 v0, v0, v22
	v_and_b32_e32 v22, 0xffff0000, v32
	global_load_dwordx4 v[30:33], v[98:99], off
	global_load_dwordx4 v[48:51], v[98:99], off offset:16
	global_load_dwordx4 v[52:55], v[100:101], off offset:16
	global_load_dwordx4 v[56:59], v[98:99], off offset:128
	global_load_dwordx4 v[60:63], v[100:101], off offset:128
	global_load_dwordx4 v[64:67], v[98:99], off offset:144
	global_load_dwordx4 v[68:71], v[100:101], off offset:144
	global_load_dwordx4 v[72:75], v[98:99], off offset:256
	global_load_dwordx4 v[76:79], v[100:101], off offset:256
	global_load_dwordx4 v[80:83], v[98:99], off offset:272
	global_load_dwordx4 v[84:87], v[100:101], off offset:272
	global_load_dwordx4 v[88:91], v[98:99], off offset:384
	global_load_dwordx4 v[92:95], v[100:101], off offset:384
	global_load_dwordx4 v[128:131], v[98:99], off offset:400
	global_load_dwordx4 v[132:135], v[100:101], off offset:400
	v_add_f32_e32 v26, v1, v0
	v_pk_mul_f32 v[0:1], v[22:23], v[22:23]
	s_nop 0
	v_pk_fma_f32 v[0:1], v[24:25], v[24:25], v[0:1]
	s_nop 0
	v_add_f32_e32 v0, v0, v26
	v_add_f32_e32 v0, v1, v0
	ds_bpermute_b32 v1, v152, v0
	s_waitcnt lgkmcnt(0)
	v_add_f32_e32 v0, v0, v1
	ds_bpermute_b32 v1, v153, v0
	s_waitcnt lgkmcnt(0)
	v_add_f32_e32 v0, v0, v1
	v_fmamk_f32 v0, v0, 0x3c000000, v164
	v_cmp_gt_f32_e32 vcc, s33, v0
	v_mul_f32_e32 v1, 0x4b800000, v0
	s_nop 0
	v_cndmask_b32_e32 v0, v0, v1, vcc
	v_rsq_f32_e32 v0, v0
	s_nop 0
	v_mul_f32_e32 v1, 0x45800000, v0
	v_cndmask_b32_e32 v0, v0, v1, vcc
	v_mul_f32_e32 v26, 0x3e0293ee, v0
	v_mul_f32_e32 v0, v26, v29
	v_mul_f32_e32 v1, v26, v38
	v_mul_f32_e32 v29, v26, v40
	v_mul_f32_e32 v2, v26, v2
	v_mul_f32_e32 v4, v26, v4
	v_mul_f32_e32 v3, v26, v3
	v_mul_f32_e32 v27, v26, v27
	v_mul_f32_e32 v5, v26, v5
	v_mul_f32_e32 v21, v26, v21
	v_mul_f32_e32 v6, v26, v6
	v_mul_f32_e32 v20, v26, v20
	v_mul_f32_e32 v7, v26, v7
	v_mul_f32_e32 v18, v26, v18
	v_mul_f32_e32 v8, v26, v8
	v_mul_f32_e32 v9, v26, v9
	v_mul_f32_e32 v12, v26, v12
	v_mul_f32_e32 v10, v26, v10
	v_mul_f32_e32 v11, v26, v11
	v_mov_b32_e32 v38, v119
	v_mov_b32_e32 v40, v119
	s_waitcnt vmcnt(0)
; __device__ __forceinline__ unsigned cvt_pk_bf16(float lo, float hi) { unsigned r; asm("v_cvt_pk_bf16_f32 %0, %1, %2" : "=v"(r) : "v"(lo), "v"(hi)); return r; }
; __device__ __forceinline__ float lo_bf(unsigned u) { return __uint_as_float(u << 16); }
; __device__ __forceinline__ float hi_bf(unsigned u) { return __uint_as_float(u & 0xffff0000u); }
; __device__ __forceinline__ void attn_phase(const Params& p, int l, bf16_t* PROJ, LAS unsigned char* L) {
;     ...
;             for (int ks = 0; ks < 4; ++ks) { const float* gp = gq + ks * 32 + fq * 8; const float* gkp = gk + ks * 32 + fq * 8; u32x4 w;
; #pragma unroll
;                 for (int e = 0; e < 4; ++e) w[e] = cvt_pk_bf16(lo_bf(raw[ks][e]) * rs * gp[2 * e] * gkp[2 * e], hi_bf(raw[ks][e]) * rs * gp[2 * e + 1] * gkp[2 * e + 1]);
;                 aq[ks] = __builtin_bit_cast(bf16x8, w); }
;         }
;         f32x4 O[8]; float mrow[4], lsum[4];
; #pragma unroll
;         for (int e = 0; e < 8; ++e) O[e] = (f32x4){0.f, 0.f, 0.f, 0.f};
; #pragma unroll
;         for (int j = 0; j < 4; ++j) { mrow[j] = -1e30f; lsum[j] = 0.f; }
	v_mul_f32_e32 v0, v30, v0
	v_mul_f32_e32 v1, v31, v1
	v_mul_f32_e32 v0, v34, v0
	v_mul_f32_e32 v1, v35, v1
	v_cvt_pk_bf16_f32 v0, v0, v1
	v_mul_f32_e32 v1, v26, v39
	v_mul_f32_e32 v1, v32, v1
	v_mul_f32_e32 v29, v33, v29
	s_waitcnt vmcnt(0)
	v_mov_b32_e32 v30, v48
	v_mov_b32_e32 v31, v49
	v_mov_b32_e32 v32, v50
	v_mov_b32_e32 v33, v51
	v_mul_f32_e32 v1, v36, v1
	v_mul_f32_e32 v29, v37, v29
	v_mov_b32_e32 v34, v52
	v_mov_b32_e32 v35, v53
	v_mov_b32_e32 v36, v54
	v_mov_b32_e32 v37, v55
	v_cvt_pk_bf16_f32 v1, v1, v29
	v_mul_f32_e32 v29, v26, v41
	v_mov_b32_e32 v39, v119
	v_mov_b32_e32 v41, v119
	s_waitcnt vmcnt(1)
	v_mul_f32_e32 v29, v30, v29
	v_mul_f32_e32 v2, v31, v2
	v_mul_f32_e32 v4, v32, v4
	v_mul_f32_e32 v3, v33, v3
	v_mov_b32_e32 v30, v56
	v_mov_b32_e32 v31, v57
	v_mov_b32_e32 v32, v58
	v_mov_b32_e32 v33, v59
	s_waitcnt vmcnt(1)
	v_mul_f32_e32 v29, v34, v29
	v_mul_f32_e32 v2, v35, v2
	v_mul_f32_e32 v4, v36, v4
	v_mul_f32_e32 v3, v37, v3
	v_mov_b32_e32 v34, v60
	v_mov_b32_e32 v35, v61
	v_mov_b32_e32 v36, v62
	v_mov_b32_e32 v37, v63
	v_cvt_pk_bf16_f32 v3, v4, v3
	v_mul_f32_e32 v4, v26, v42
	v_cvt_pk_bf16_f32 v2, v29, v2
	v_mov_b32_e32 v42, v119
	s_waitcnt vmcnt(1)
	v_mul_f32_e32 v4, v30, v4
	v_mul_f32_e32 v27, v31, v27
	v_mul_f32_e32 v5, v5, v33
	s_waitcnt vmcnt(0)
	v_mul_f32_e32 v4, v34, v4
	v_mul_f32_e32 v27, v35, v27
	v_cvt_pk_bf16_f32 v4, v4, v27
	v_mul_f32_e32 v27, v26, v28
	v_mov_b32_e32 v28, v64
	v_mov_b32_e32 v29, v65
	v_mov_b32_e32 v30, v66
	v_mov_b32_e32 v31, v67
	v_mul_f32_e32 v27, v32, v27
	v_mov_b32_e32 v32, v68
	v_mov_b32_e32 v33, v69
	v_mov_b32_e32 v34, v70
	v_mov_b32_e32 v35, v71
	v_mul_f32_e32 v27, v36, v27
	v_mul_f32_e32 v5, v37, v5
	v_cvt_pk_bf16_f32 v5, v27, v5
	v_mov_b32_e32 v27, v119
	v_mov_b32_e32 v37, v119
	v_mov_b32_e32 v36, v119
	s_waitcnt vmcnt(1)
	v_mul_f32_e32 v21, v21, v28
	v_mul_f32_e32 v6, v6, v29
	v_mul_f32_e32 v20, v20, v30
	v_mul_f32_e32 v7, v7, v31
	v_mov_b32_e32 v28, v72
	v_mov_b32_e32 v29, v73
	v_mov_b32_e32 v30, v74
	v_mov_b32_e32 v31, v75
	s_waitcnt vmcnt(1)
	v_mul_f32_e32 v21, v32, v21
	v_mul_f32_e32 v6, v33, v6
	v_mul_f32_e32 v20, v34, v20
	v_mul_f32_e32 v7, v35, v7
	v_mov_b32_e32 v32, v76
	v_mov_b32_e32 v33, v77
	v_mov_b32_e32 v34, v78
	v_mov_b32_e32 v35, v79
	v_cvt_pk_bf16_f32 v6, v21, v6
	v_cvt_pk_bf16_f32 v7, v20, v7
	s_waitcnt vmcnt(1)
	v_mul_f32_e32 v18, v18, v28
	v_mul_f32_e32 v8, v8, v29
	v_mul_f32_e32 v9, v9, v31
	s_waitcnt vmcnt(0)
	v_mul_f32_e32 v18, v32, v18
	v_mul_f32_e32 v8, v33, v8
	v_cvt_pk_bf16_f32 v8, v18, v8
	v_mul_f32_e32 v18, v26, v19
	v_mul_f32_e32 v18, v18, v30
	v_mul_f32_e32 v18, v34, v18
	v_mul_f32_e32 v9, v35, v9
	v_cvt_pk_bf16_f32 v9, v18, v9
	v_mov_b32_e32 v18, v80
	v_mov_b32_e32 v19, v81
	v_mov_b32_e32 v20, v82
	v_mov_b32_e32 v21, v83
	v_mov_b32_e32 v28, v84
	v_mov_b32_e32 v29, v85
	v_mov_b32_e32 v30, v86
	v_mov_b32_e32 v31, v87
	v_mov_b32_e32 v35, v119
	v_mov_b32_e32 v34, v119
	v_mov_b32_e32 v33, v119
	v_mov_b32_e32 v32, v119
	s_waitcnt vmcnt(1)
	v_mul_f32_e32 v12, v12, v18
	v_mul_f32_e32 v10, v10, v19
	s_waitcnt vmcnt(0)
	v_mul_f32_e32 v12, v28, v12
	v_mul_f32_e32 v10, v29, v10
	v_cvt_pk_bf16_f32 v10, v12, v10
	v_mul_f32_e32 v12, v26, v13
	v_mul_f32_e32 v12, v12, v20
	v_mul_f32_e32 v11, v11, v21
	v_mov_b32_e32 v18, v88
	v_mov_b32_e32 v19, v89
	v_mov_b32_e32 v20, v90
	v_mov_b32_e32 v21, v91
	v_mul_f32_e32 v12, v30, v12
	v_mul_f32_e32 v11, v31, v11
	v_mov_b32_e32 v28, v92
	v_mov_b32_e32 v29, v93
	v_mov_b32_e32 v30, v94
	v_mov_b32_e32 v31, v95
	v_cvt_pk_bf16_f32 v11, v12, v11
	v_mul_f32_e32 v12, v26, v16
	v_mul_f32_e32 v13, v26, v14
	v_mul_f32_e32 v14, v26, v15
	s_waitcnt vmcnt(1)
	v_mul_f32_e32 v12, v12, v18
	v_mul_f32_e32 v13, v13, v19
	v_mul_f32_e32 v14, v14, v21
	s_waitcnt vmcnt(0)
	v_mul_f32_e32 v12, v28, v12
	v_mul_f32_e32 v13, v29, v13
	v_cvt_pk_bf16_f32 v12, v12, v13
	v_mul_f32_e32 v13, v26, v17
	v_mul_f32_e32 v13, v13, v20
	v_mul_f32_e32 v13, v30, v13
	v_mul_f32_e32 v14, v31, v14
	v_cvt_pk_bf16_f32 v13, v13, v14
	v_mov_b32_e32 v14, v128
	v_mov_b32_e32 v15, v129
	v_mov_b32_e32 v16, v130
	v_mov_b32_e32 v17, v131
	v_mul_f32_e32 v18, v26, v24
	v_mov_b32_e32 v24, v119
	v_mov_b32_e32 v31, v119
	v_mov_b32_e32 v30, v119
	v_mov_b32_e32 v29, v119
	v_mov_b32_e32 v28, v119
	s_waitcnt vmcnt(0)
	v_mul_f32_e32 v14, v18, v14
	v_mov_b32_e32 v18, v132
	v_mov_b32_e32 v19, v133
	v_mov_b32_e32 v20, v134
	v_mov_b32_e32 v21, v135
	s_waitcnt vmcnt(0)
	v_mul_f32_e32 v14, v18, v14
	v_mul_f32_e32 v18, v26, v22
	v_mul_f32_e32 v15, v18, v15
	v_mul_f32_e32 v15, v19, v15
	v_cvt_pk_bf16_f32 v14, v14, v15
	v_mul_f32_e32 v15, v26, v25
	v_mul_f32_e32 v15, v15, v16
	v_mul_f32_e32 v16, v26, v23
	v_mul_f32_e32 v16, v16, v17
	v_mul_f32_e32 v15, v20, v15
	v_mul_f32_e32 v16, v21, v16
	v_cvt_pk_bf16_f32 v15, v15, v16
	v_mov_b32_e32 v19, v119
	v_mov_b32_e32 v18, v119
	v_mov_b32_e32 v17, v119
	v_mov_b32_e32 v16, v119
	v_mov_b32_e32 v23, v119
	v_mov_b32_e32 v22, v119
	v_mov_b32_e32 v21, v119
	v_mov_b32_e32 v20, v119
	v_mov_b32_e32 v26, v119
	v_mov_b32_e32 v25, v119
	s_cbranch_scc0 .LBB0_335
; __device__ __forceinline__ void attn_phase(const Params& p, int l, bf16_t* PROJ, LAS unsigned char* L) {
;     ...
;         f32x4 O[8]; float mrow[4], lsum[4];
; #pragma unroll
;         for (int e = 0; e < 8; ++e) O[e] = (f32x4){0.f, 0.f, 0.f, 0.f};
; #pragma unroll
;         for (int j = 0; j < 4; ++j) { mrow[j] = -1e30f; lsum[j] = 0.f; }
;         const int jstart = n >= 8 ? 0 : 8 - n;
;         u32x4 kr[4]; u32x4 vr[2][2];
;     ...
;         ATT_LOAD(n - 8 + jstart);
	s_add_i32 s20, s3, s20
	s_lshl_b32 s40, s20, 6
	s_lshl_b32 s34, s36, 7
	s_add_i32 s41, s40, 0xfffffe00
	s_or_b32 s35, s34, 0x80
	s_mul_i32 s21, s41, 0x5000
	s_mul_hi_i32 s20, s41, 0x5000
	s_add_u32 s21, s14, s21
	s_addc_u32 s22, s15, s20
	s_add_u32 s20, s21, 0x1000
	s_addc_u32 s21, s22, 0
	s_lshl_b32 s22, s36, 8
	s_add_u32 s22, s20, s22
	s_addc_u32 s23, s21, 0
	v_lshlrev_b32_e32 v136, 1, v102
	v_lshl_add_u64 v[20:21], s[22:23], 0, v[136:137]
	v_lshl_add_u64 v[22:23], v[20:21], 0, v[104:105]
	v_lshl_add_u64 v[20:21], v[20:21], 0, v[106:107]
	global_load_dwordx4 v[48:51], v[22:23], off
	global_load_dwordx4 v[52:55], v[20:21], off
	v_lshl_add_u64 v[20:21], s[20:21], 0, v[136:137]
	v_add_lshl_u32 v120, s36, v161, 7
	v_add_lshl_u32 v16, s36, v182, 7
	v_add_lshl_u32 v122, s36, v184, 7
	v_add_lshl_u32 v18, s36, v185, 7
	v_lshl_add_u64 v[22:23], v[20:21], 0, v[104:105]
	s_lshl_b32 s36, s35, 1
	v_lshl_add_u64 v[20:21], v[20:21], 0, v[106:107]
	v_lshl_add_u64 v[22:23], v[22:23], 0, s[36:37]
	v_lshl_add_u64 v[20:21], v[20:21], 0, s[36:37]
	v_ashrrev_i32_e32 v19, 31, v18
	global_load_dwordx4 v[72:75], v[22:23], off
	global_load_dwordx4 v[76:79], v[20:21], off
	v_or_b32_e32 v22, s41, v186
	v_mov_b64_e32 v[20:21], s[14:15]
	v_mad_i64_i32 v[22:23], s[20:21], v22, s62, v[20:21]
	v_lshlrev_b64 v[18:19], 1, v[18:19]
	v_or_b32_e32 v24, s41, v181
	v_ashrrev_i32_e32 v123, 31, v122
	v_lshl_add_u64 v[22:23], v[22:23], 0, v[18:19]
	v_mad_i64_i32 v[24:25], s[20:21], v24, s62, v[20:21]
	v_lshl_add_u64 v[22:23], v[22:23], 0, v[136:137]
	v_lshl_add_u64 v[26:27], v[122:123], 1, v[24:25]
	v_ashrrev_i32_e32 v17, 31, v16
	v_lshl_add_u64 v[26:27], v[26:27], 0, v[136:137]
	global_load_dwordx4 v[56:59], v[22:23], off offset:2048
	global_load_dwordx4 v[60:63], v[26:27], off offset:2048
	v_or_b32_e32 v22, s41, v183
	v_mad_i64_i32 v[20:21], s[20:21], v22, s62, v[20:21]
	v_lshlrev_b64 v[16:17], 1, v[16:17]
	v_ashrrev_i32_e32 v121, 31, v120
	v_lshl_add_u64 v[20:21], v[20:21], 0, v[16:17]
	v_lshl_add_u64 v[20:21], v[20:21], 0, v[136:137]
	v_lshl_add_u64 v[22:23], v[120:121], 1, v[24:25]
	v_lshl_add_u64 v[22:23], v[22:23], 0, v[136:137]
	global_load_dwordx4 v[64:67], v[20:21], off offset:2048
	global_load_dwordx4 v[68:71], v[22:23], off offset:2048
	s_lshl_b32 s20, s3, 6
	v_mov_b32_e32 v44, 0
	v_lshl_add_u64 v[124:125], v[110:111], 0, v[16:17]
	v_lshl_add_u64 v[126:127], v[110:111], 0, v[18:19]
	v_subrev_u32_e32 v113, s20, v195
	s_add_i32 s22, s40, 0xfffffe40
	v_mov_b32_e32 v217, 0xf149f2ca
	s_lshl_b32 s23, s34, 1
	s_lshl_b32 s36, s35, 1
	v_mov_b32_e32 v218, 0xf149f2ca
	v_mov_b32_e32 v219, 0xf149f2ca
	v_mov_b32_e32 v220, 0xf149f2ca
	v_mov_b32_e32 v45, v44
	v_mov_b32_e32 v46, v44
	v_mov_b32_e32 v47, v44
	v_mov_b32_e32 v40, v44
	v_mov_b32_e32 v41, v44
	v_mov_b32_e32 v42, v44
	v_mov_b32_e32 v43, v44
	v_mov_b32_e32 v36, v44
	v_mov_b32_e32 v37, v44
	v_mov_b32_e32 v38, v44
	v_mov_b32_e32 v39, v44
	v_mov_b32_e32 v32, v44
	v_mov_b32_e32 v33, v44
	v_mov_b32_e32 v34, v44
	v_mov_b32_e32 v35, v44
	v_mov_b32_e32 v28, v44
	v_mov_b32_e32 v29, v44
	v_mov_b32_e32 v30, v44
	v_mov_b32_e32 v31, v44
	v_mov_b32_e32 v24, v44
	v_mov_b32_e32 v25, v44
	v_mov_b32_e32 v26, v44
	v_mov_b32_e32 v27, v44
	v_mov_b32_e32 v20, v44
	v_mov_b32_e32 v21, v44
	v_mov_b32_e32 v22, v44
	v_mov_b32_e32 v23, v44
	v_mov_b32_e32 v16, v44
	v_mov_b32_e32 v17, v44
	v_mov_b32_e32 v18, v44
	v_mov_b32_e32 v19, v44
	v_mov_b32_e32 v116, v44
	v_mov_b32_e32 v117, v44
	v_mov_b32_e32 v118, v44
	v_mov_b32_e32 v119, v44
